# v128 plus nt on the final-norm phase (last-use bf16 row loads, never-re-read f32 output stores) and on the phase-3 w_in(l+1) bf16 stores
# speedup vs baseline: 1.0086x; 1.0086x over previous
.LBB0_496:
	s_waitcnt vmcnt(0)
	ds_write2_b32 v48, v8, v9 offset1:66
	ds_write2_b32 v48, v10, v11 offset0:132 offset1:198
	v_add_u32_e32 v8, 0x400, v48
	ds_write2_b32 v8, v12, v13 offset0:8 offset1:74
	ds_write2_b32 v8, v14, v15 offset0:140 offset1:206
	v_add_u32_e32 v8, 0x800, v48
	ds_write2_b32 v8, v16, v17 offset0:16 offset1:82
	ds_write2_b32 v8, v18, v19 offset0:148 offset1:214
	v_add_u32_e32 v8, 0xc00, v48
	ds_write2_b32 v8, v22, v23 offset0:24 offset1:90
	ds_write2_b32 v8, v26, v27 offset0:156 offset1:222
	v_add_u32_e32 v8, 0x1000, v48
	ds_write2_b32 v8, v28, v29 offset0:32 offset1:98
	ds_write2_b32 v8, v30, v31 offset0:164 offset1:230
	v_add_u32_e32 v8, 0x1400, v48
	ds_write2_b32 v8, v32, v33 offset0:40 offset1:106
	ds_write2_b32 v8, v34, v35 offset0:172 offset1:238
	v_add_u32_e32 v8, 0x1800, v48
	ds_write2_b32 v8, v36, v37 offset0:48 offset1:114
	ds_write2_b32 v8, v38, v39 offset0:180 offset1:246
	v_add_u32_e32 v8, 0x1c00, v48
	ds_write2_b32 v8, v40, v41 offset0:56 offset1:122
	ds_write2_b32 v8, v42, v43 offset0:188 offset1:254
	s_waitcnt lgkmcnt(0)
	ds_read2_b32 v[12:13], v47 offset0:33 offset1:41
	ds_read2_b32 v[14:15], v47 offset1:8
	ds_read2_b32 v[16:17], v47 offset0:66 offset1:74
	ds_read2_b32 v[18:19], v47 offset0:99 offset1:107
	ds_read2_b32 v[20:21], v47 offset0:132 offset1:140
	ds_read2_b32 v[22:23], v47 offset0:165 offset1:173
	ds_read2_b32 v[24:25], v47 offset0:198 offset1:206
	ds_read2_b32 v[26:27], v47 offset0:231 offset1:239
	v_add_u32_e32 v30, s3, v46
	s_ashr_i32 s51, s50, 31
	v_ashrrev_i32_e32 v31, 31, v30
	v_lshl_add_u64 v[28:29], s[50:51], 1, v[6:7]
	v_lshlrev_b64 v[32:33], 12, v[30:31]
	s_waitcnt lgkmcnt(6)
	v_cvt_pk_bf16_f32 v8, v14, v12
	s_waitcnt lgkmcnt(4)
	v_cvt_pk_bf16_f32 v9, v16, v18
	s_waitcnt lgkmcnt(2)
	v_cvt_pk_bf16_f32 v10, v20, v22
	s_waitcnt lgkmcnt(0)
	v_cvt_pk_bf16_f32 v11, v24, v26
	v_lshl_add_u64 v[32:33], v[28:29], 0, v[32:33]
	v_add_u32_e32 v12, 8, v30
	global_store_dwordx4 v[32:33], v[8:11], off nt
	v_readlane_b32 s4, v255, 17
	s_add_i32 s2, s2, s4
	v_cvt_pk_bf16_f32 v8, v15, v13
	v_ashrrev_i32_e32 v13, 31, v12
	v_cvt_pk_bf16_f32 v9, v17, v19
	v_cvt_pk_bf16_f32 v10, v21, v23
	v_cvt_pk_bf16_f32 v11, v25, v27
	v_lshlrev_b64 v[12:13], 12, v[12:13]
	ds_read2_b32 v[14:15], v47 offset0:49 offset1:57
	ds_read2_b32 v[16:17], v47 offset0:16 offset1:24
	ds_read2_b32 v[18:19], v47 offset0:82 offset1:90
	ds_read2_b32 v[20:21], v47 offset0:115 offset1:123
	ds_read2_b32 v[22:23], v47 offset0:148 offset1:156
	ds_read2_b32 v[24:25], v47 offset0:181 offset1:189
	ds_read2_b32 v[26:27], v47 offset0:214 offset1:222
	ds_read2_b32 v[32:33], v47 offset0:247 offset1:255
	v_lshl_add_u64 v[12:13], v[28:29], 0, v[12:13]
	global_store_dwordx4 v[12:13], v[8:11], off nt
	v_add_u32_e32 v12, 16, v30
	v_ashrrev_i32_e32 v13, 31, v12
	v_lshlrev_b64 v[12:13], 12, v[12:13]
	s_waitcnt lgkmcnt(6)
	v_cvt_pk_bf16_f32 v8, v16, v14
	s_waitcnt lgkmcnt(4)
	v_cvt_pk_bf16_f32 v9, v18, v20
	s_waitcnt lgkmcnt(2)
	v_cvt_pk_bf16_f32 v10, v22, v24
	s_waitcnt lgkmcnt(0)
	v_cvt_pk_bf16_f32 v11, v26, v32
	v_lshl_add_u64 v[12:13], v[28:29], 0, v[12:13]
	global_store_dwordx4 v[12:13], v[8:11], off nt
	v_add_u32_e32 v12, 24, v30
	v_ashrrev_i32_e32 v13, 31, v12
	v_lshlrev_b64 v[12:13], 12, v[12:13]
	v_cvt_pk_bf16_f32 v8, v17, v15
	v_cvt_pk_bf16_f32 v9, v19, v21
	v_cvt_pk_bf16_f32 v10, v23, v25
	v_cvt_pk_bf16_f32 v11, v27, v33
	v_lshl_add_u64 v[12:13], v[28:29], 0, v[12:13]
	global_store_dwordx4 v[12:13], v[8:11], off nt
	s_waitcnt lgkmcnt(0)
	s_add_i32 s0, s0, s1
	s_cmpk_lt_i32 s2, 0x1b00
	v_readlane_b32 s5, v255, 18
	s_cbranch_scc0 .LBB0_563

.LBB0_1229:
	global_load_dwordx2 v[26:27], v[12:13], off offset:-4 nt
	global_load_dwordx4 v[22:25], v[14:15], off
	v_add_u32_e32 v21, 0x100, v21
	v_cmp_lt_u32_e32 vcc, s28, v21
	v_lshl_add_u64 v[14:15], v[14:15], 0, s[16:17]
	v_lshl_add_u64 v[12:13], v[12:13], 0, s[24:25]
	s_or_b64 s[12:13], vcc, s[12:13]
	s_waitcnt vmcnt(1)
	v_lshlrev_b32_e32 v28, 16, v26
	v_and_b32_e32 v29, 0xffff0000, v26
	v_lshlrev_b32_e32 v26, 16, v27
	v_and_b32_e32 v27, 0xffff0000, v27
	v_pk_mul_f32 v[28:29], v[18:19], v[28:29]
	v_pk_mul_f32 v[26:27], v[18:19], v[26:27]
	s_waitcnt vmcnt(0)
	v_pk_mul_f32 v[22:23], v[28:29], v[22:23]
	v_pk_mul_f32 v[24:25], v[24:25], v[26:27]
	global_store_dwordx4 v[16:17], v[22:25], off nt
	v_lshl_add_u64 v[16:17], v[16:17], 0, s[16:17]
	s_andn2_b64 exec, exec, s[12:13]
	s_cbranch_execnz .LBB0_1229
	s_or_b64 exec, exec, s[12:13]
	s_add_i32 s20, s20, s48
	v_lshl_add_u64 v[6:7], v[6:7], 0, s[0:1]
	s_cmpk_gt_i32 s20, 0x1fff
	v_lshl_add_u64 v[10:11], v[10:11], 0, s[2:3]
	s_cbranch_scc0 .LBB0_1228
